# indexer appends: dropped the always-zero sign-extension ops of the 14-bit key index (key index is below 16384 by construction)
# baseline (speedup 1.0000x reference)
; __device__ __forceinline__ unsigned lds_add(LAS unsigned* p, unsigned v) { return __hip_atomic_fetch_add(p, v, __ATOMIC_RELAXED, __HIP_MEMORY_SCOPE_WORKGROUP); }
; __device__ void indexer_item(LAS unsigned char* lds, const bf16_t* Qi, const bf16_t* Ki, const float* Wi, unsigned* maskout, int qt) {
;     ...
;         for (int j = 0; j < 8; ++j) if (keyi[j] <= tq && k32[j] > thr) {
;             const unsigned pos = lds_add(cnt + q, 1u);
;             if (pos < 512u) cand[q * 512 + pos] = ((u64)k32[j] << 16) | (u64)(16383 - keyi[j]);
;         }
.LBB0_728:
	s_waitcnt lgkmcnt(0)
	v_cmp_gt_u32_e32 vcc, v154, v101
	s_and_b64 s[24:25], s[24:25], vcc
	v_cmp_gt_u32_e32 vcc, v44, v101
	s_and_b64 s[22:23], s[22:23], vcc
	v_cmp_gt_u32_e32 vcc, v42, v101
	s_and_b64 s[20:21], s[20:21], vcc
	v_cmp_gt_u32_e32 vcc, v40, v101
	s_and_b64 s[18:19], s[18:19], vcc
	v_cmp_gt_u32_e32 vcc, v38, v101
	s_and_b64 s[16:17], s[16:17], vcc
	v_cmp_gt_u32_e32 vcc, v36, v101
	s_and_b64 s[14:15], s[14:15], vcc
	v_cmp_gt_u32_e32 vcc, v34, v101
	s_and_b64 s[12:13], s[12:13], vcc
	v_cmp_gt_u32_e32 vcc, v32, v101
	s_and_b64 s[10:11], s[10:11], vcc
	s_or_b64 vcc, s[24:25], s[22:23]
	s_or_b64 vcc, vcc, s[20:21]
	s_or_b64 vcc, vcc, s[18:19]
	s_or_b64 vcc, vcc, s[16:17]
	s_or_b64 vcc, vcc, s[14:15]
	s_or_b64 vcc, vcc, s[12:13]
	s_or_b64 vcc, vcc, s[10:11]
	s_cbranch_scc0 .Lix_noapp
	s_mov_b64 s[26:27], exec
	s_mov_b64 exec, s[24:25]
	ds_add_rtn_u32 v240, v81, v180
	s_mov_b64 exec, s[22:23]
	ds_add_rtn_u32 v241, v81, v180
	s_mov_b64 exec, s[20:21]
	ds_add_rtn_u32 v242, v81, v180
	s_mov_b64 exec, s[18:19]
	ds_add_rtn_u32 v243, v81, v180
	s_mov_b64 exec, s[16:17]
	ds_add_rtn_u32 v244, v81, v180
	s_mov_b64 exec, s[14:15]
	ds_add_rtn_u32 v245, v81, v180
	s_mov_b64 exec, s[12:13]
	ds_add_rtn_u32 v246, v81, v180
	s_mov_b64 exec, s[10:11]
	ds_add_rtn_u32 v247, v81, v180
	s_mov_b64 exec, s[26:27]
	v_sub_u32_e32 v33, 0x3fff, v43
	v_lshl_or_b32 v248, v154, 16, v33
	v_lshrrev_b32_e32 v249, 16, v154
	v_sub_u32_e32 v33, 0x3ffe, v43
	v_lshl_or_b32 v250, v44, 16, v33
	v_lshrrev_b32_e32 v251, 16, v44
	v_sub_u32_e32 v33, 0x3fff, v41
	v_lshl_or_b32 v252, v42, 16, v33
	v_lshrrev_b32_e32 v253, 16, v42
	v_sub_u32_e32 v33, 0x3fff, v107
	v_lshl_or_b32 v254, v40, 16, v33
	v_lshrrev_b32_e32 v255, 16, v40
	v_sub_u32_e32 v33, 0x3fff, v106
	v_lshl_or_b32 v46, v38, 16, v33
	v_lshrrev_b32_e32 v47, 16, v38
	v_sub_u32_e32 v33, 0x3fff, v35
	v_lshl_or_b32 v44, v36, 16, v33
	v_lshrrev_b32_e32 v45, 16, v36
	v_sub_u32_e32 v33, 0x3fff, v105
	v_lshl_or_b32 v42, v34, 16, v33
	v_lshrrev_b32_e32 v43, 16, v34
	v_sub_u32_e32 v33, 0x3fff, v104
	v_lshl_or_b32 v40, v32, 16, v33
	v_lshrrev_b32_e32 v41, 16, v32
	s_waitcnt lgkmcnt(7)
	s_mov_b64 exec, s[24:25]
	v_cmp_gt_u32_e32 vcc, s73, v240
	s_and_b64 exec, exec, vcc
	v_lshl_add_u32 v240, v240, 3, v102
	ds_write_b64 v240, v[248:249] offset:35072
	s_waitcnt lgkmcnt(7)
	s_mov_b64 exec, s[22:23]
	v_cmp_gt_u32_e32 vcc, s73, v241
	s_and_b64 exec, exec, vcc
	v_lshl_add_u32 v241, v241, 3, v102
	ds_write_b64 v241, v[250:251] offset:35072
	s_waitcnt lgkmcnt(7)
	s_mov_b64 exec, s[20:21]
	v_cmp_gt_u32_e32 vcc, s73, v242
	s_and_b64 exec, exec, vcc
	v_lshl_add_u32 v242, v242, 3, v102
	ds_write_b64 v242, v[252:253] offset:35072
	s_waitcnt lgkmcnt(7)
	s_mov_b64 exec, s[18:19]
	v_cmp_gt_u32_e32 vcc, s73, v243
	s_and_b64 exec, exec, vcc
	v_lshl_add_u32 v243, v243, 3, v102
	ds_write_b64 v243, v[254:255] offset:35072
	s_waitcnt lgkmcnt(7)
	s_mov_b64 exec, s[16:17]
	v_cmp_gt_u32_e32 vcc, s73, v244
	s_and_b64 exec, exec, vcc
	v_lshl_add_u32 v244, v244, 3, v102
	ds_write_b64 v244, v[46:47] offset:35072
	s_waitcnt lgkmcnt(7)
	s_mov_b64 exec, s[14:15]
	v_cmp_gt_u32_e32 vcc, s73, v245
	s_and_b64 exec, exec, vcc
	v_lshl_add_u32 v245, v245, 3, v102
	ds_write_b64 v245, v[44:45] offset:35072
	s_waitcnt lgkmcnt(7)
	s_mov_b64 exec, s[12:13]
	v_cmp_gt_u32_e32 vcc, s73, v246
	s_and_b64 exec, exec, vcc
	v_lshl_add_u32 v246, v246, 3, v102
	ds_write_b64 v246, v[42:43] offset:35072
	s_waitcnt lgkmcnt(7)
	s_mov_b64 exec, s[10:11]
	v_cmp_gt_u32_e32 vcc, s73, v247
	s_and_b64 exec, exec, vcc
	v_lshl_add_u32 v247, v247, 3, v102
	ds_write_b64 v247, v[40:41] offset:35072
	s_mov_b64 exec, s[26:27]
